# v11 plus GEMM phase prologue de-serialisation: second group of 6 LDS-DMA stage loads issued before the first counted wait (vmcnt 2 -> 8) in 13 GEMM phases
# baseline (speedup 1.0000x reference)
; #define PG8_STAGE(bufoff, gbase, voff) do { _Pragma("unroll") for (int _i = 0; _i < 2; ++_i) \
;         __builtin_amdgcn_global_load_lds((const unsigned*)((const char*)(gbase) + (voff)[_i]), (PG8_LAS unsigned*)(lds + (bufoff) + ldsw + _i * 8192), 16, 0, 0); } while (0)
; #define PG8_WAIT_V(n) asm volatile("s_waitcnt vmcnt(" #n ")" ::: "memory")
; #define PG8_BAR __builtin_amdgcn_s_barrier()
; template <class Epi, class Sched, bool ALIGN_EPI = false, bool SP2 = false>
; __device__ __forceinline__ void gemm_phase(PG8_LAS unsigned char* lds, const Gemm g, const Sched& S, const Epi& E) {
;     ...
;     const unsigned ldsw = (unsigned)wid * 1024u;
;     const int aoff = lds_byte(wr * 64 + fr, fq * 8), boff = lds_byte(wc * 32 + fr, fq * 8);
;     ...
;         PG8_STAGE(PG8_SB(0, 0), cB, voffB); PG8_STAGE(PG8_SB(0, 1), cB + hstep, voffB); PG8_STAGE(PG8_SA(0, 0), cA, voffA); PG8_STAGE(PG8_SA(0, 1), cA + hstep, voffA);
;         if (wr == 1) PG8_BAR;
;         PG8_WAIT_V(2); PG8_BAR;
;         PG8_STAGE(PG8_SB(1, 0), cB + kstep, voffB); PG8_STAGE(PG8_SA(1, 0), cA + kstep, voffA); PG8_STAGE(PG8_SB(1, 1), cB + hstep + kstep, voffB);
;         PG8_WAIT_V(6); PG8_BAR;
.LBB0_67:
	s_lshl_b32 s6, s6, 5
	s_and_b32 s30, s6, 0x60
	s_mov_b64 s[6:7], 0x80
	s_add_i32 m0, s33, 0x18000
	v_lshl_add_u64 v[6:7], v[6:7], 0, s[6:7]
	s_lshl_b32 s25, s24, 13
	s_lshl_b32 s31, s30, 7
	global_load_lds_dwordx4 v[6:7], off
	v_lshl_add_u64 v[4:5], v[4:5], 0, s[6:7]
	s_add_i32 m0, s33, 0x1a000
	s_add_i32 s50, s33, 0x8000
	s_add_i32 s51, s33, 0xa000
	global_load_lds_dwordx4 v[4:5], off
	v_lshl_add_u64 v[0:1], v[0:1], 0, s[6:7]
	s_mov_b32 m0, s50
	s_add_u32 s28, s42, 0x80080
	global_load_lds_dwordx4 v[0:1], off
	v_lshl_add_u64 v[0:1], v[2:3], 0, s[6:7]
	s_mov_b32 m0, s51
	s_addc_u32 s29, s43, 0
	global_load_lds_dwordx4 v[0:1], off
	s_add_i32 m0, s33, 0x1c000
	v_lshl_add_u64 v[0:1], s[28:29], 0, v[132:133]
	global_load_lds_dwordx4 v[0:1], off
	v_lshl_add_u64 v[0:1], s[28:29], 0, v[128:129]
	s_add_i32 m0, s33, 0x1e000
	s_cmpk_lt_u32 s5, 0x100
	global_load_lds_dwordx4 v[0:1], off
	v_lshrrev_b32_e32 v1, 1, v9
	v_and_b32_e32 v1, 24, v1
	v_and_b32_e32 v0, 15, v9
	v_lshlrev_b32_e32 v2, 1, v1
	v_lshl_or_b32 v144, s24, 6, v0
	v_lshl_or_b32 v0, v0, 6, v2
	v_lshlrev_b32_e32 v2, 2, v9
	v_and_b32_e32 v2, 32, v2
	v_bitop3_b32 v3, v0, s25, v2 bitop3:0xde
	v_bitop3_b32 v145, v0, s31, v2 bitop3:0xde
	v_lshlrev_b32_e32 v0, 15, v13
	v_and_b32_e32 v0, 0xffff0000, v0
	v_or_b32_e32 v146, s30, v1
	v_lshl_add_u32 v0, v12, 12, v0
	v_and_b32_e32 v1, 1, v13
	v_lshl_or_b32 v0, v1, 6, v0
	v_lshl_add_u32 v136, v14, 1, v0
	v_lshlrev_b32_e32 v0, 15, v8
	v_and_b32_e32 v0, 0xffff0000, v0
	s_waitcnt vmcnt(8)
	s_barrier
	s_waitcnt vmcnt(6)
	v_lshl_add_u32 v0, v10, 12, v0
	v_and_b32_e32 v1, 1, v8
	s_cselect_b64 s[24:25], -1, 0
	v_lshl_or_b32 v0, v1, 6, v0
	s_add_i32 s54, 0, 0x10000
	s_add_i32 s55, 0, 0x14000
	s_sext_i32_i16 s57, s4
	s_ashr_i32 s52, s76, 31
	s_mov_b32 s53, s76
	v_mov_b32_e32 v137, v133
	v_lshl_add_u32 v138, v11, 1, v0
	v_mov_b32_e32 v139, v133
	v_mov_b64_e32 v[140:141], 0xb00
	v_mov_b64_e32 v[142:143], 0xaff
	v_add_u32_e32 v147, s54, v145
	v_add_u32_e32 v148, s55, v145
	v_add_u32_e32 v149, 0, v3
	s_movk_i32 s56, 0x2c00
	s_barrier
	s_branch .LBB0_70

; #define PG8_STAGE(bufoff, gbase, voff) do { _Pragma("unroll") for (int _i = 0; _i < 2; ++_i) \
;         __builtin_amdgcn_global_load_lds((const unsigned*)((const char*)(gbase) + (voff)[_i]), (PG8_LAS unsigned*)(lds + (bufoff) + ldsw + _i * 8192), 16, 0, 0); } while (0)
; #define PG8_WAIT_V(n) asm volatile("s_waitcnt vmcnt(" #n ")" ::: "memory")
; #define PG8_BAR __builtin_amdgcn_s_barrier()
; template <class Epi, class Sched, bool ALIGN_EPI = false, bool SP2 = false>
; __device__ __forceinline__ void gemm_phase(PG8_LAS unsigned char* lds, const Gemm g, const Sched& S, const Epi& E) {
;     ...
;     const unsigned ldsw = (unsigned)wid * 1024u;
;     const int aoff = lds_byte(wr * 64 + fr, fq * 8), boff = lds_byte(wc * 32 + fr, fq * 8);
;     ...
;         PG8_STAGE(PG8_SB(0, 0), cB, voffB); PG8_STAGE(PG8_SB(0, 1), cB + hstep, voffB); PG8_STAGE(PG8_SA(0, 0), cA, voffA); PG8_STAGE(PG8_SA(0, 1), cA + hstep, voffA);
;         if (wr == 1) PG8_BAR;
;         PG8_WAIT_V(2); PG8_BAR;
;         PG8_STAGE(PG8_SB(1, 0), cB + kstep, voffB); PG8_STAGE(PG8_SA(1, 0), cA + kstep, voffA); PG8_STAGE(PG8_SB(1, 1), cB + hstep + kstep, voffB);
;         PG8_WAIT_V(6); PG8_BAR;
.LBB0_135:
	s_lshl_b32 s6, s6, 5
	v_and_b32_e32 v17, 15, v16
	s_and_b32 s37, s6, 0x60
	v_lshl_or_b32 v144, s7, 6, v17
	s_lshl_b32 s7, s7, 13
	s_lshl_b32 s6, s37, 7
	s_sext_i32_i8 s57, s28
	s_add_u32 s28, s90, 0x19100000
	s_mov_b64 s[30:31], 0x80
	s_addc_u32 s29, s91, 0
	s_add_i32 m0, s33, 0x18000
	v_lshl_add_u64 v[6:7], v[6:7], 0, s[30:31]
	global_load_lds_dwordx4 v[6:7], off
	v_lshl_add_u64 v[2:3], v[2:3], 0, s[30:31]
	s_add_i32 m0, s33, 0x1a000
	s_add_i32 s50, s33, 0x8000
	s_add_i32 s51, s33, 0xa000
	global_load_lds_dwordx4 v[2:3], off
	v_lshl_add_u64 v[0:1], v[0:1], 0, s[30:31]
	s_mov_b32 m0, s50
	s_add_u32 s34, s40, 0x160080
	global_load_lds_dwordx4 v[0:1], off
	v_lshl_add_u64 v[0:1], v[4:5], 0, s[30:31]
	s_mov_b32 m0, s51
	s_addc_u32 s35, s41, 0
	global_load_lds_dwordx4 v[0:1], off
	s_add_i32 m0, s33, 0x1c000
	v_lshl_add_u64 v[0:1], s[34:35], 0, v[132:133]
	global_load_lds_dwordx4 v[0:1], off
	v_lshl_add_u64 v[0:1], s[34:35], 0, v[128:129]
	s_add_i32 m0, s33, 0x1e000
	v_lshrrev_b32_e32 v18, 1, v16
	global_load_lds_dwordx4 v[0:1], off
	v_and_b32_e32 v18, 24, v18
	v_lshrrev_b32_e32 v1, 1, v13
	v_mul_lo_u32 v0, v12, s5
	v_lshlrev_b32_e32 v19, 1, v18
	v_lshlrev_b32_e32 v16, 2, v16
	v_mad_u64_u32 v[0:1], s[42:43], v1, s36, v[0:1]
	v_lshl_or_b32 v17, v17, 6, v19
	v_and_b32_e32 v16, 32, v16
	v_or_b32_e32 v0, v0, v14
	v_bitop3_b32 v19, v17, s7, v16 bitop3:0xde
	v_bitop3_b32 v145, v17, s6, v16 bitop3:0xde
	s_mov_b64 s[6:7], 0x160080
	v_add_lshl_u32 v0, v0, v15, 1
	v_mov_b32_e32 v1, v133
	v_lshl_add_u64 v[136:137], v[0:1], 0, s[6:7]
	v_lshrrev_b32_e32 v1, 1, v8
	v_mul_lo_u32 v0, v9, s5
	s_cmpk_lt_u32 s4, 0x100
	v_mad_u64_u32 v[0:1], s[4:5], v1, s36, v[0:1]
	s_waitcnt vmcnt(8)
	s_barrier
	s_waitcnt vmcnt(6)
	v_or_b32_e32 v0, v0, v10
	s_cselect_b64 s[34:35], -1, 0
	v_add_lshl_u32 v0, v0, v11, 1
	v_mov_b32_e32 v1, v133
	s_add_i32 s55, 0, 0x10000
	s_add_i32 s56, 0, 0x14000
	s_ashr_i32 s52, s76, 31
	s_mov_b32 s53, s76
	v_or_b32_e32 v146, s37, v18
	v_lshl_add_u64 v[138:139], v[0:1], 0, s[6:7]
	v_mov_b64_e32 v[140:141], 0x200
	v_mov_b64_e32 v[142:143], 0x1ff
	v_add_u32_e32 v147, s55, v145
	v_add_u32_e32 v148, s56, v145
	v_add_u32_e32 v149, 0, v19
	s_barrier
	s_branch .LBB0_138

; #define PG8_STAGE(bufoff, gbase, voff) do { _Pragma("unroll") for (int _i = 0; _i < 2; ++_i) \
;         __builtin_amdgcn_global_load_lds((const unsigned*)((const char*)(gbase) + (voff)[_i]), (PG8_LAS unsigned*)(lds + (bufoff) + ldsw + _i * 8192), 16, 0, 0); } while (0)
; #define PG8_WAIT_V(n) asm volatile("s_waitcnt vmcnt(" #n ")" ::: "memory")
; #define PG8_BAR __builtin_amdgcn_s_barrier()
; template <class Epi, class Sched, bool ALIGN_EPI = false, bool SP2 = false>
; __device__ __forceinline__ void gemm_phase(PG8_LAS unsigned char* lds, const Gemm g, const Sched& S, const Epi& E) {
;     ...
;     const unsigned ldsw = (unsigned)wid * 1024u;
;     const int aoff = lds_byte(wr * 64 + fr, fq * 8), boff = lds_byte(wc * 32 + fr, fq * 8);
;     ...
;         PG8_STAGE(PG8_SB(0, 0), cB, voffB); PG8_STAGE(PG8_SB(0, 1), cB + hstep, voffB); PG8_STAGE(PG8_SA(0, 0), cA, voffA); PG8_STAGE(PG8_SA(0, 1), cA + hstep, voffA);
;         if (wr == 1) PG8_BAR;
;         PG8_WAIT_V(2); PG8_BAR;
;         PG8_STAGE(PG8_SB(1, 0), cB + kstep, voffB); PG8_STAGE(PG8_SA(1, 0), cA + kstep, voffA); PG8_STAGE(PG8_SB(1, 1), cB + hstep + kstep, voffB);
;         PG8_WAIT_V(6); PG8_BAR;
.LBB0_271:
	s_lshl_b32 s6, s6, 5
	s_and_b32 s26, s6, 0x60
	s_mov_b64 s[6:7], 0x80
	s_add_i32 m0, s21, 0x18000
	v_lshl_add_u64 v[6:7], v[6:7], 0, s[6:7]
	s_lshl_b32 s9, s8, 13
	s_lshl_b32 s27, s26, 7
	global_load_lds_dwordx4 v[6:7], off
	v_lshl_add_u64 v[4:5], v[4:5], 0, s[6:7]
	s_add_i32 m0, s21, 0x1a000
	s_add_i32 s45, s21, 0x8000
	s_add_i32 s46, s21, 0xa000
	global_load_lds_dwordx4 v[4:5], off
	v_lshl_add_u64 v[0:1], v[0:1], 0, s[6:7]
	s_mov_b32 m0, s45
	s_add_u32 s22, s36, 0x80080
	global_load_lds_dwordx4 v[0:1], off
	v_lshl_add_u64 v[0:1], v[2:3], 0, s[6:7]
	s_mov_b32 m0, s46
	s_addc_u32 s23, s37, 0
	global_load_lds_dwordx4 v[0:1], off
	s_add_i32 m0, s21, 0x1c000
	v_lshl_add_u64 v[0:1], s[22:23], 0, v[132:133]
	global_load_lds_dwordx4 v[0:1], off
	v_lshl_add_u64 v[0:1], s[22:23], 0, v[128:129]
	s_add_i32 m0, s21, 0x1e000
	s_cmpk_lt_u32 s5, 0x100
	global_load_lds_dwordx4 v[0:1], off
	v_lshrrev_b32_e32 v1, 1, v9
	v_and_b32_e32 v1, 24, v1
	v_and_b32_e32 v0, 15, v9
	v_lshlrev_b32_e32 v2, 1, v1
	v_lshl_or_b32 v144, s8, 6, v0
	v_lshl_or_b32 v0, v0, 6, v2
	v_lshlrev_b32_e32 v2, 2, v9
	v_and_b32_e32 v2, 32, v2
	v_bitop3_b32 v3, v0, s9, v2 bitop3:0xde
	v_bitop3_b32 v145, v0, s27, v2 bitop3:0xde
	v_lshlrev_b32_e32 v0, 15, v13
	v_and_b32_e32 v0, 0xffff0000, v0
	v_or_b32_e32 v146, s26, v1
	v_lshl_add_u32 v0, v12, 12, v0
	v_and_b32_e32 v1, 1, v13
	v_lshl_or_b32 v0, v1, 6, v0
	v_lshl_add_u32 v136, v14, 1, v0
	v_lshlrev_b32_e32 v0, 15, v8
	v_and_b32_e32 v0, 0xffff0000, v0
	s_waitcnt vmcnt(8)
	s_barrier
	s_waitcnt vmcnt(6)
	v_lshl_add_u32 v0, v10, 12, v0
	v_and_b32_e32 v1, 1, v8
	s_cselect_b64 s[8:9], -1, 0
	v_lshl_or_b32 v0, v1, 6, v0
	s_add_i32 s49, 0, 0x10000
	s_add_i32 s50, 0, 0x14000
	s_sext_i32_i8 s52, s4
	s_ashr_i32 s47, s76, 31
	s_mov_b32 s48, s76
	v_mov_b32_e32 v137, v133
	v_lshl_add_u32 v138, v11, 1, v0
	v_mov_b32_e32 v139, v133
	v_mov_b64_e32 v[140:141], 0x140
	v_mov_b64_e32 v[142:143], 0x13f
	v_add_u32_e32 v147, s49, v145
	v_add_u32_e32 v148, s50, v145
	v_add_u32_e32 v149, 0, v3
	s_movk_i32 s51, 0xa00
	s_barrier
	s_branch .LBB0_274

; #define PG8_STAGE(bufoff, gbase, voff) do { _Pragma("unroll") for (int _i = 0; _i < 2; ++_i) \
;         __builtin_amdgcn_global_load_lds((const unsigned*)((const char*)(gbase) + (voff)[_i]), (PG8_LAS unsigned*)(lds + (bufoff) + ldsw + _i * 8192), 16, 0, 0); } while (0)
; #define PG8_WAIT_V(n) asm volatile("s_waitcnt vmcnt(" #n ")" ::: "memory")
; #define PG8_BAR __builtin_amdgcn_s_barrier()
; template <class Epi, class Sched, bool ALIGN_EPI = false, bool SP2 = false>
; __device__ __forceinline__ void gemm_phase(PG8_LAS unsigned char* lds, const Gemm g, const Sched& S, const Epi& E) {
;     ...
;     const unsigned ldsw = (unsigned)wid * 1024u;
;     const int aoff = lds_byte(wr * 64 + fr, fq * 8), boff = lds_byte(wc * 32 + fr, fq * 8);
;     ...
;         PG8_STAGE(PG8_SB(0, 0), cB, voffB); PG8_STAGE(PG8_SB(0, 1), cB + hstep, voffB); PG8_STAGE(PG8_SA(0, 0), cA, voffA); PG8_STAGE(PG8_SA(0, 1), cA + hstep, voffA);
;         if (wr == 1) PG8_BAR;
;         PG8_WAIT_V(2); PG8_BAR;
;         PG8_STAGE(PG8_SB(1, 0), cB + kstep, voffB); PG8_STAGE(PG8_SA(1, 0), cA + kstep, voffA); PG8_STAGE(PG8_SB(1, 1), cB + hstep + kstep, voffB);
;         PG8_WAIT_V(6); PG8_BAR;
.LBB0_396:
	s_mov_b64 s[10:11], 0x80
	s_and_b32 s52, s2, 3
	s_add_i32 m0, s46, 0x18000
	v_lshl_add_u64 v[6:7], v[6:7], 0, s[10:11]
	s_lshl_b32 s1, s5, 13
	s_lshl_b32 s6, s52, 5
	s_lshl_b32 s22, s52, 12
	global_load_lds_dwordx4 v[6:7], off
	v_lshl_add_u64 v[4:5], v[4:5], 0, s[10:11]
	s_add_i32 m0, s46, 0x1a000
	s_add_i32 s50, s46, 0x8000
	s_add_i32 s51, s46, 0xa000
	global_load_lds_dwordx4 v[4:5], off
	v_lshl_add_u64 v[0:1], v[0:1], 0, s[10:11]
	s_mov_b32 m0, s50
	s_add_u32 s20, s38, 0x20080
	global_load_lds_dwordx4 v[0:1], off
	v_lshl_add_u64 v[0:1], v[2:3], 0, s[10:11]
	s_mov_b32 m0, s51
	s_addc_u32 s21, s39, 0
	global_load_lds_dwordx4 v[0:1], off
	s_add_i32 m0, s46, 0x1c000
	v_lshl_add_u64 v[0:1], s[20:21], 0, v[132:133]
	global_load_lds_dwordx4 v[0:1], off
	v_lshl_add_u64 v[0:1], s[20:21], 0, v[128:129]
	s_add_i32 m0, s46, 0x1e000
	s_sext_i32_i8 s2, s4
	global_load_lds_dwordx4 v[0:1], off
	v_lshrrev_b32_e32 v1, 1, v10
	v_and_b32_e32 v138, 24, v1
	v_and_b32_e32 v0, 15, v10
	v_lshlrev_b32_e32 v1, 1, v138
	v_lshl_or_b32 v139, s5, 6, v0
	v_lshl_or_b32 v0, v0, 6, v1
	v_lshlrev_b32_e32 v1, 2, v10
	v_and_b32_e32 v1, 32, v1
	v_lshlrev_b32_e32 v136, 2, v138
	v_bitop3_b32 v2, v0, s1, v1 bitop3:0xde
	v_bitop3_b32 v170, v0, s22, v1 bitop3:0xde
	v_lshl_add_u64 v[0:1], s[90:91], 0, v[136:137]
	s_mov_b64 s[4:5], 0x200000
	v_lshl_add_u64 v[140:141], v[0:1], 0, s[4:5]
	s_mov_b64 s[4:5], 0x400000
	v_lshl_add_u64 v[142:143], v[0:1], 0, s[4:5]
	v_lshlrev_b32_e32 v0, 13, v13
	v_and_b32_e32 v0, 0xffffc000, v0
	v_lshl_add_u32 v0, v12, 10, v0
	v_and_b32_e32 v1, 1, v13
	v_lshl_or_b32 v0, v1, 6, v0
	v_lshl_add_u32 v144, v14, 1, v0
	v_lshlrev_b32_e32 v0, 13, v8
	s_orn2_b32 s52, s52, 31
	v_and_b32_e32 v0, 0xffffc000, v0
	s_waitcnt vmcnt(8)
	s_barrier
	s_waitcnt vmcnt(6)
	s_cmpk_lt_u32 s3, 0x100
	v_lshl_add_u32 v0, v9, 10, v0
	v_and_b32_e32 v1, 1, v8
	s_cselect_b64 s[20:21], -1, 0
	v_lshl_or_b32 v0, v1, 6, v0
	s_add_i32 s55, 0, 0x10000
	s_add_i32 s56, 0, 0x14000
	s_ashr_i32 s53, s76, 31
	s_mov_b32 s54, s76
	v_mov_b32_e32 v145, v137
	v_lshl_add_u32 v146, v11, 1, v0
	v_mov_b32_e32 v147, v137
	v_mov_b64_e32 v[148:149], 0x300
	v_mov_b64_e32 v[150:151], 0x2ff
	v_add_u32_e32 v171, s55, v170
	v_add_u32_e32 v172, s56, v170
	v_add_u32_e32 v173, 0, v2
	s_mov_b32 s22, 0x3dd53b94
	s_movk_i32 s57, 0x1800
	s_lshl_b32 s6, s6, 1
	s_mov_b32 s58, s7
	s_barrier
	s_branch .LBB0_399

; #define PG8_STAGE(bufoff, gbase, voff) do { _Pragma("unroll") for (int _i = 0; _i < 2; ++_i) \
;         __builtin_amdgcn_global_load_lds((const unsigned*)((const char*)(gbase) + (voff)[_i]), (PG8_LAS unsigned*)(lds + (bufoff) + ldsw + _i * 8192), 16, 0, 0); } while (0)
; #define PG8_WAIT_V(n) asm volatile("s_waitcnt vmcnt(" #n ")" ::: "memory")
; #define PG8_BAR __builtin_amdgcn_s_barrier()
; template <class Epi, class Sched, bool ALIGN_EPI = false, bool SP2 = false>
; __device__ __forceinline__ void gemm_phase(PG8_LAS unsigned char* lds, const Gemm g, const Sched& S, const Epi& E) {
;     ...
;     const unsigned ldsw = (unsigned)wid * 1024u;
;     const int aoff = lds_byte(wr * 64 + fr, fq * 8), boff = lds_byte(wc * 32 + fr, fq * 8);
;     ...
;         PG8_STAGE(PG8_SB(0, 0), cB, voffB); PG8_STAGE(PG8_SB(0, 1), cB + hstep, voffB); PG8_STAGE(PG8_SA(0, 0), cA, voffA); PG8_STAGE(PG8_SA(0, 1), cA + hstep, voffA);
;         if (wr == 1) PG8_BAR;
;         PG8_WAIT_V(2); PG8_BAR;
;         PG8_STAGE(PG8_SB(1, 0), cB + kstep, voffB); PG8_STAGE(PG8_SA(1, 0), cA + kstep, voffA); PG8_STAGE(PG8_SB(1, 1), cB + hstep + kstep, voffB);
;         PG8_WAIT_V(6); PG8_BAR;
.LBB0_420:
	s_lshl_b32 s6, s6, 5
	s_and_b32 s26, s6, 0x60
	s_mov_b64 s[6:7], 0x80
	s_add_i32 m0, s23, 0x18000
	v_lshl_add_u64 v[6:7], v[6:7], 0, s[6:7]
	s_lshl_b32 s9, s8, 13
	s_lshl_b32 s27, s26, 7
	global_load_lds_dwordx4 v[6:7], off
	v_lshl_add_u64 v[4:5], v[4:5], 0, s[6:7]
	s_add_i32 m0, s23, 0x1a000
	s_add_i32 s47, s23, 0x8000
	s_add_i32 s48, s23, 0xa000
	global_load_lds_dwordx4 v[4:5], off
	v_lshl_add_u64 v[0:1], v[0:1], 0, s[6:7]
	s_mov_b32 m0, s47
	s_add_u32 s20, s38, 0x20080
	global_load_lds_dwordx4 v[0:1], off
	v_lshl_add_u64 v[0:1], v[2:3], 0, s[6:7]
	s_mov_b32 m0, s48
	s_addc_u32 s21, s39, 0
	global_load_lds_dwordx4 v[0:1], off
	s_add_i32 m0, s23, 0x1c000
	v_lshl_add_u64 v[0:1], s[20:21], 0, v[130:131]
	global_load_lds_dwordx4 v[0:1], off
	v_lshl_add_u64 v[0:1], s[20:21], 0, v[134:135]
	s_add_i32 m0, s23, 0x1e000
	s_cmpk_lt_u32 s5, 0x100
	global_load_lds_dwordx4 v[0:1], off
	v_lshrrev_b32_e32 v1, 1, v8
	v_and_b32_e32 v1, 24, v1
	v_and_b32_e32 v0, 15, v8
	v_lshlrev_b32_e32 v2, 1, v1
	v_lshl_or_b32 v137, s8, 6, v0
	v_lshl_or_b32 v0, v0, 6, v2
	v_lshlrev_b32_e32 v2, 2, v8
	v_and_b32_e32 v2, 32, v2
	v_bitop3_b32 v3, v0, s9, v2 bitop3:0xde
	v_bitop3_b32 v146, v0, s27, v2 bitop3:0xde
	v_lshlrev_b32_e32 v0, 13, v9
	v_and_b32_e32 v0, 0xffffc000, v0
	v_or_b32_e32 v136, s26, v1
	v_lshl_add_u32 v0, v10, 10, v0
	v_and_b32_e32 v1, 1, v9
	v_lshl_or_b32 v0, v1, 6, v0
	v_lshl_add_u32 v138, v11, 1, v0
	v_lshlrev_b32_e32 v0, 13, v12
	v_and_b32_e32 v0, 0xffffc000, v0
	s_waitcnt vmcnt(8)
	s_barrier
	s_waitcnt vmcnt(6)
	v_lshl_add_u32 v0, v13, 10, v0
	v_and_b32_e32 v1, 1, v12
	s_cselect_b64 s[8:9], -1, 0
	v_lshl_or_b32 v0, v1, 6, v0
	s_add_i32 s51, 0, 0x10000
	s_add_i32 s52, 0, 0x14000
	s_sext_i32_i8 s53, s4
	s_ashr_i32 s49, s76, 31
	s_mov_b32 s50, s76
	v_mov_b32_e32 v139, v131
	v_lshl_add_u32 v140, v14, 1, v0
	v_mov_b32_e32 v141, v131
	v_mov_b64_e32 v[142:143], 0x400
	v_mov_b64_e32 v[144:145], 0x3ff
	v_add_u32_e32 v147, s51, v146
	v_add_u32_e32 v148, s52, v146
	v_add_u32_e32 v149, 0, v3
	s_mov_b64 s[20:21], 0xb0000
	s_barrier
	s_branch .LBB0_423

; #define PG8_STAGE(bufoff, gbase, voff) do { _Pragma("unroll") for (int _i = 0; _i < 2; ++_i) \
;         __builtin_amdgcn_global_load_lds((const unsigned*)((const char*)(gbase) + (voff)[_i]), (PG8_LAS unsigned*)(lds + (bufoff) + ldsw + _i * 8192), 16, 0, 0); } while (0)
; #define PG8_WAIT_V(n) asm volatile("s_waitcnt vmcnt(" #n ")" ::: "memory")
; #define PG8_BAR __builtin_amdgcn_s_barrier()
; template <class Epi, class Sched, bool ALIGN_EPI = false, bool SP2 = false>
; __device__ __forceinline__ void gemm_phase(PG8_LAS unsigned char* lds, const Gemm g, const Sched& S, const Epi& E) {
;     ...
;     const unsigned ldsw = (unsigned)wid * 1024u;
;     const int aoff = lds_byte(wr * 64 + fr, fq * 8), boff = lds_byte(wc * 32 + fr, fq * 8);
;     ...
;         PG8_STAGE(PG8_SB(0, 0), cB, voffB); PG8_STAGE(PG8_SB(0, 1), cB + hstep, voffB); PG8_STAGE(PG8_SA(0, 0), cA, voffA); PG8_STAGE(PG8_SA(0, 1), cA + hstep, voffA);
;         if (wr == 1) PG8_BAR;
;         PG8_WAIT_V(2); PG8_BAR;
;         PG8_STAGE(PG8_SB(1, 0), cB + kstep, voffB); PG8_STAGE(PG8_SA(1, 0), cA + kstep, voffA); PG8_STAGE(PG8_SB(1, 1), cB + hstep + kstep, voffB);
;         PG8_WAIT_V(6); PG8_BAR;
.LBB0_787:
	s_lshl_b32 s1, s5, 5
	s_mov_b64 s[8:9], 0x80
	s_and_b32 s5, s1, 0x60
	s_add_i32 m0, s30, 0x18000
	v_lshl_add_u64 v[6:7], v[6:7], 0, s[8:9]
	s_lshl_b32 s12, s3, 13
	s_lshl_b32 s13, s5, 7
	global_load_lds_dwordx4 v[6:7], off
	v_lshl_add_u64 v[4:5], v[4:5], 0, s[8:9]
	s_add_i32 m0, s30, 0x1a000
	s_add_i32 s37, s30, 0x8000
	s_add_i32 s38, s30, 0xa000
	global_load_lds_dwordx4 v[4:5], off
	v_lshl_add_u64 v[0:1], v[0:1], 0, s[8:9]
	s_mov_b32 m0, s37
	s_add_u32 s10, s22, 0x80080
	global_load_lds_dwordx4 v[0:1], off
	v_lshl_add_u64 v[0:1], v[2:3], 0, s[8:9]
	s_mov_b32 m0, s38
	s_addc_u32 s11, s23, 0
	global_load_lds_dwordx4 v[0:1], off
	s_add_i32 m0, s30, 0x1c000
	v_lshl_add_u64 v[0:1], s[10:11], 0, v[142:143]
	global_load_lds_dwordx4 v[0:1], off
	v_lshl_add_u64 v[0:1], s[10:11], 0, v[146:147]
	s_add_i32 m0, s30, 0x1e000
	s_cmpk_lt_u32 s2, 0x100
	global_load_lds_dwordx4 v[0:1], off
	v_lshrrev_b32_e32 v1, 1, v8
	v_and_b32_e32 v1, 24, v1
	v_and_b32_e32 v0, 15, v8
	v_lshlrev_b32_e32 v2, 1, v1
	v_lshl_or_b32 v166, s3, 6, v0
	v_lshl_or_b32 v0, v0, 6, v2
	v_lshlrev_b32_e32 v2, 2, v8
	v_and_b32_e32 v2, 32, v2
	v_bitop3_b32 v3, v0, s12, v2 bitop3:0xde
	v_bitop3_b32 v167, v0, s13, v2 bitop3:0xde
	v_or_b32_e32 v0, s5, v1
	v_lshlrev_b32_e32 v1, 15, v9
	v_and_b32_e32 v1, 0xffff0000, v1
	v_lshl_add_u32 v1, v10, 12, v1
	v_and_b32_e32 v2, 1, v9
	v_lshl_or_b32 v1, v2, 6, v1
	v_lshl_add_u32 v154, v11, 1, v1
	v_lshlrev_b32_e32 v1, 15, v12
	v_and_b32_e32 v1, 0xffff0000, v1
	s_waitcnt vmcnt(8)
	s_barrier
	s_waitcnt vmcnt(6)
	v_lshlrev_b32_e32 v148, 1, v0
	v_readlane_b32 s44, v232, 8
	v_lshl_add_u32 v1, v13, 12, v1
	v_and_b32_e32 v2, 1, v12
	s_cselect_b64 s[10:11], -1, 0
	v_lshl_add_u64 v[150:151], s[62:63], 0, v[148:149]
	v_lshlrev_b32_e32 v148, 2, v0
	v_readlane_b32 s58, v232, 22
	v_readlane_b32 s59, v232, 23
	v_lshl_or_b32 v1, v2, 6, v1
	s_add_i32 s41, 0, 0x10000
	s_add_i32 s42, 0, 0x14000
	s_sext_i32_i8 s1, s4
	s_ashr_i32 s39, s76, 31
	s_mov_b32 s40, s76
	v_lshl_add_u64 v[152:153], s[58:59], 0, v[148:149]
	v_mov_b32_e32 v155, v149
	v_lshl_add_u32 v156, v14, 1, v1
	v_mov_b32_e32 v157, v149
	v_mov_b64_e32 v[158:159], 0x200
	v_mov_b64_e32 v[160:161], 0x1ff
	v_add_u32_e32 v168, s41, v167
	v_add_u32_e32 v169, s42, v167
	v_add_u32_e32 v170, 0, v3
	v_mov_b32_e32 v171, 0x358637bd
	v_lshlrev_b32_e32 v148, 1, v0
	s_barrier
	v_readlane_b32 s45, v232, 9
	v_readlane_b32 s46, v232, 10
	v_readlane_b32 s47, v232, 11
	v_readlane_b32 s48, v232, 12
	v_readlane_b32 s49, v232, 13
	v_readlane_b32 s50, v232, 14
	v_readlane_b32 s51, v232, 15
	v_readlane_b32 s52, v232, 16
	v_readlane_b32 s53, v232, 17
	v_readlane_b32 s54, v232, 18
	v_readlane_b32 s55, v232, 19
	v_readlane_b32 s56, v232, 20
	v_readlane_b32 s57, v232, 21
	s_branch .LBB0_790

; #define PG8_STAGE(bufoff, gbase, voff) do { _Pragma("unroll") for (int _i = 0; _i < 2; ++_i) \
;         __builtin_amdgcn_global_load_lds((const unsigned*)((const char*)(gbase) + (voff)[_i]), (PG8_LAS unsigned*)(lds + (bufoff) + ldsw + _i * 8192), 16, 0, 0); } while (0)
; #define PG8_WAIT_V(n) asm volatile("s_waitcnt vmcnt(" #n ")" ::: "memory")
; #define PG8_BAR __builtin_amdgcn_s_barrier()
; template <class Epi, class Sched, bool ALIGN_EPI = false, bool SP2 = false>
; __device__ __forceinline__ void gemm_phase(PG8_LAS unsigned char* lds, const Gemm g, const Sched& S, const Epi& E) {
;     ...
;     const unsigned ldsw = (unsigned)wid * 1024u;
;     const int aoff = lds_byte(wr * 64 + fr, fq * 8), boff = lds_byte(wc * 32 + fr, fq * 8);
;     ...
;         PG8_STAGE(PG8_SB(0, 0), cB, voffB); PG8_STAGE(PG8_SB(0, 1), cB + hstep, voffB); PG8_STAGE(PG8_SA(0, 0), cA, voffA); PG8_STAGE(PG8_SA(0, 1), cA + hstep, voffA);
;         if (wr == 1) PG8_BAR;
;         PG8_WAIT_V(2); PG8_BAR;
;         PG8_STAGE(PG8_SB(1, 0), cB + kstep, voffB); PG8_STAGE(PG8_SA(1, 0), cA + kstep, voffA); PG8_STAGE(PG8_SB(1, 1), cB + hstep + kstep, voffB);
;         PG8_WAIT_V(6); PG8_BAR;
.LBB0_811:
	s_lshl_b32 s4, s4, 5
	s_mov_b64 s[8:9], 0x80
	s_and_b32 s12, s4, 0x60
	s_add_i32 m0, s25, 0x18000
	v_lshl_add_u64 v[6:7], v[6:7], 0, s[8:9]
	s_and_b32 s2, s0, 0xff
	s_lshl_b32 s0, s1, 13
	s_lshl_b32 s10, s12, 7
	global_load_lds_dwordx4 v[6:7], off
	v_lshl_add_u64 v[2:3], v[2:3], 0, s[8:9]
	s_add_i32 m0, s25, 0x1a000
	s_add_i32 s42, s25, 0x8000
	s_add_i32 s43, s25, 0xa000
	global_load_lds_dwordx4 v[2:3], off
	v_lshl_add_u64 v[0:1], v[0:1], 0, s[8:9]
	s_mov_b32 m0, s42
	s_add_u32 s4, s28, 0x80080
	global_load_lds_dwordx4 v[0:1], off
	v_lshl_add_u64 v[0:1], v[4:5], 0, s[8:9]
	s_mov_b32 m0, s43
	s_addc_u32 s5, s29, 0
	global_load_lds_dwordx4 v[0:1], off
	s_add_i32 m0, s25, 0x1c000
	v_lshl_add_u64 v[0:1], s[4:5], 0, v[130:131]
	global_load_lds_dwordx4 v[0:1], off
	v_lshl_add_u64 v[0:1], s[4:5], 0, v[134:135]
	s_add_i32 m0, s25, 0x1e000
	s_cmpk_lt_u32 s3, 0x100
	global_load_lds_dwordx4 v[0:1], off
	v_lshrrev_b32_e32 v1, 1, v8
	v_and_b32_e32 v1, 24, v1
	v_and_b32_e32 v0, 15, v8
	v_lshlrev_b32_e32 v2, 1, v1
	v_lshl_or_b32 v152, s1, 6, v0
	v_lshl_or_b32 v0, v0, 6, v2
	v_lshlrev_b32_e32 v2, 2, v8
	v_and_b32_e32 v2, 32, v2
	v_bitop3_b32 v3, v0, s0, v2 bitop3:0xde
	v_bitop3_b32 v153, v0, s10, v2 bitop3:0xde
	v_lshlrev_b32_e32 v0, 15, v9
	v_and_b32_e32 v0, 0xffff0000, v0
	v_or_b32_e32 v154, s12, v1
	v_lshl_add_u32 v0, v10, 12, v0
	v_and_b32_e32 v1, 1, v9
	v_lshl_or_b32 v0, v1, 6, v0
	v_lshl_add_u32 v138, v11, 1, v0
	v_lshlrev_b32_e32 v0, 15, v12
	v_and_b32_e32 v0, 0xffff0000, v0
	s_waitcnt vmcnt(8)
	s_barrier
	s_waitcnt vmcnt(6)
	v_lshl_add_u32 v0, v13, 12, v0
	v_and_b32_e32 v1, 1, v12
	s_cselect_b64 s[10:11], -1, 0
	v_lshl_or_b32 v0, v1, 6, v0
	s_add_i32 s46, 0, 0x10000
	s_add_i32 s47, 0, 0x14000
	s_ashr_i32 s44, s76, 31
	s_mov_b32 s45, s76
	v_mov_b32_e32 v139, v137
	v_lshl_add_u32 v140, v14, 1, v0
	v_mov_b32_e32 v141, v137
	v_mov_b64_e32 v[142:143], 0x200
	v_mov_b64_e32 v[144:145], 0x1ff
	v_add_u32_e32 v155, s46, v153
	v_add_u32_e32 v156, s47, v153
	v_add_u32_e32 v157, 0, v3
	s_mov_b32 s48, 0x80000
	s_mov_b64 s[12:13], 0x90000
	s_mov_b32 s49, 0x90000
	s_mov_b64 s[14:15], 0xa0000
	s_mov_b32 s50, 0xa0000
	s_mov_b64 s[16:17], 0xb0000
	s_mov_b32 s3, 0xb0000
	s_barrier
	s_waitcnt vmcnt(0)
	s_branch .LBB0_814

; #define PG8_STAGE(bufoff, gbase, voff) do { _Pragma("unroll") for (int _i = 0; _i < 2; ++_i) \
;         __builtin_amdgcn_global_load_lds((const unsigned*)((const char*)(gbase) + (voff)[_i]), (PG8_LAS unsigned*)(lds + (bufoff) + ldsw + _i * 8192), 16, 0, 0); } while (0)
; #define PG8_WAIT_V(n) asm volatile("s_waitcnt vmcnt(" #n ")" ::: "memory")
; #define PG8_BAR __builtin_amdgcn_s_barrier()
; template <class Epi, class Sched, bool ALIGN_EPI = false, bool SP2 = false>
; __device__ __forceinline__ void gemm_phase(PG8_LAS unsigned char* lds, const Gemm g, const Sched& S, const Epi& E) {
;     ...
;     const unsigned ldsw = (unsigned)wid * 1024u;
;     const int aoff = lds_byte(wr * 64 + fr, fq * 8), boff = lds_byte(wc * 32 + fr, fq * 8);
;     ...
;         PG8_STAGE(PG8_SB(0, 0), cB, voffB); PG8_STAGE(PG8_SB(0, 1), cB + hstep, voffB); PG8_STAGE(PG8_SA(0, 0), cA, voffA); PG8_STAGE(PG8_SA(0, 1), cA + hstep, voffA);
;         if (wr == 1) PG8_BAR;
;         PG8_WAIT_V(2); PG8_BAR;
;         PG8_STAGE(PG8_SB(1, 0), cB + kstep, voffB); PG8_STAGE(PG8_SA(1, 0), cA + kstep, voffA); PG8_STAGE(PG8_SB(1, 1), cB + hstep + kstep, voffB);
;         PG8_WAIT_V(6); PG8_BAR;
.LBB0_835:
	s_lshl_b32 s0, s0, 5
	s_and_b32 s14, s0, 0x60
	s_mov_b64 s[0:1], 0x80
	s_add_i32 m0, s27, 0x18000
	v_lshl_add_u64 v[6:7], v[6:7], 0, s[0:1]
	s_lshl_b32 s11, s10, 13
	s_lshl_b32 s15, s14, 7
	global_load_lds_dwordx4 v[6:7], off
	v_lshl_add_u64 v[2:3], v[2:3], 0, s[0:1]
	s_add_i32 m0, s27, 0x1a000
	s_add_i32 s2, s27, 0x8000
	s_add_i32 s3, s27, 0xa000
	global_load_lds_dwordx4 v[2:3], off
	v_lshl_add_u64 v[0:1], v[0:1], 0, s[0:1]
	s_mov_b32 m0, s2
	s_add_u32 s12, s30, 0x80080
	global_load_lds_dwordx4 v[0:1], off
	v_lshl_add_u64 v[0:1], v[4:5], 0, s[0:1]
	s_mov_b32 m0, s3
	s_addc_u32 s13, s31, 0
	global_load_lds_dwordx4 v[0:1], off
	s_add_i32 m0, s27, 0x1c000
	v_lshl_add_u64 v[0:1], s[12:13], 0, v[138:139]
	global_load_lds_dwordx4 v[0:1], off
	v_lshl_add_u64 v[0:1], s[12:13], 0, v[142:143]
	s_add_i32 m0, s27, 0x1e000
	s_cmpk_lt_u32 s5, 0x100
	global_load_lds_dwordx4 v[0:1], off
	v_lshrrev_b32_e32 v1, 1, v8
	v_and_b32_e32 v1, 24, v1
	v_and_b32_e32 v0, 15, v8
	v_lshlrev_b32_e32 v2, 1, v1
	v_lshl_or_b32 v160, s10, 6, v0
	v_lshl_or_b32 v0, v0, 6, v2
	v_lshlrev_b32_e32 v2, 2, v8
	v_and_b32_e32 v2, 32, v2
	v_bitop3_b32 v3, v0, s11, v2 bitop3:0xde
	v_bitop3_b32 v161, v0, s15, v2 bitop3:0xde
	v_lshlrev_b32_e32 v0, 15, v9
	v_and_b32_e32 v0, 0xffff0000, v0
	v_or_b32_e32 v162, s14, v1
	v_lshl_add_u32 v0, v10, 12, v0
	v_and_b32_e32 v1, 1, v9
	v_lshl_or_b32 v0, v1, 6, v0
	v_lshl_add_u32 v144, v11, 1, v0
	v_lshlrev_b32_e32 v0, 15, v12
	v_and_b32_e32 v0, 0xffff0000, v0
	s_waitcnt vmcnt(8)
	s_barrier
	s_waitcnt vmcnt(6)
	v_lshl_add_u32 v0, v13, 12, v0
	v_and_b32_e32 v1, 1, v12
	s_cselect_b64 s[10:11], -1, 0
	v_lshl_or_b32 v0, v1, 6, v0
	s_add_i32 s43, 0, 0x10000
	s_add_i32 s44, 0, 0x14000
	s_sext_i32_i8 s45, s4
	s_ashr_i32 s33, s76, 31
	s_mov_b32 s42, s76
	v_mov_b32_e32 v145, v139
	v_lshl_add_u32 v146, v14, 1, v0
	v_mov_b32_e32 v147, v139
	v_mov_b64_e32 v[148:149], 0x200
	v_mov_b64_e32 v[150:151], 0x1ff
	v_add_u32_e32 v163, s43, v161
	v_add_u32_e32 v164, s44, v161
	v_add_u32_e32 v165, 0, v3
	s_mov_b64 s[12:13], 0x90000
	s_mov_b64 s[14:15], 0xa0000
	s_mov_b64 s[16:17], 0xb0000
	s_barrier
	s_branch .LBB0_838

; #define PG8_STAGE(bufoff, gbase, voff) do { _Pragma("unroll") for (int _i = 0; _i < 2; ++_i) \
;         __builtin_amdgcn_global_load_lds((const unsigned*)((const char*)(gbase) + (voff)[_i]), (PG8_LAS unsigned*)(lds + (bufoff) + ldsw + _i * 8192), 16, 0, 0); } while (0)
; #define PG8_WAIT_V(n) asm volatile("s_waitcnt vmcnt(" #n ")" ::: "memory")
; #define PG8_BAR __builtin_amdgcn_s_barrier()
; template <class Epi, class Sched, bool ALIGN_EPI = false, bool SP2 = false>
; __device__ __forceinline__ void gemm_phase(PG8_LAS unsigned char* lds, const Gemm g, const Sched& S, const Epi& E) {
;     ...
;     const unsigned ldsw = (unsigned)wid * 1024u;
;     const int aoff = lds_byte(wr * 64 + fr, fq * 8), boff = lds_byte(wc * 32 + fr, fq * 8);
;     ...
;         PG8_STAGE(PG8_SB(0, 0), cB, voffB); PG8_STAGE(PG8_SB(0, 1), cB + hstep, voffB); PG8_STAGE(PG8_SA(0, 0), cA, voffA); PG8_STAGE(PG8_SA(0, 1), cA + hstep, voffA);
;         if (wr == 1) PG8_BAR;
;         PG8_WAIT_V(2); PG8_BAR;
;         PG8_STAGE(PG8_SB(1, 0), cB + kstep, voffB); PG8_STAGE(PG8_SA(1, 0), cA + kstep, voffA); PG8_STAGE(PG8_SB(1, 1), cB + hstep + kstep, voffB);
;         PG8_WAIT_V(6); PG8_BAR;
.LBB0_859:
	s_lshl_b32 s5, s5, 5
	s_mov_b64 s[10:11], 0x80
	s_and_b32 s5, s5, 0x60
	s_add_i32 m0, s27, 0x18000
	v_lshl_add_u64 v[6:7], v[6:7], 0, s[10:11]
	s_and_b32 s2, s0, 0xff
	s_lshl_b32 s0, s1, 13
	s_lshl_b32 s14, s5, 7
	global_load_lds_dwordx4 v[6:7], off
	v_lshl_add_u64 v[2:3], v[2:3], 0, s[10:11]
	s_add_i32 m0, s27, 0x1a000
	s_add_i32 s43, s27, 0x8000
	s_add_i32 s44, s27, 0xa000
	global_load_lds_dwordx4 v[2:3], off
	v_lshl_add_u64 v[0:1], v[0:1], 0, s[10:11]
	s_mov_b32 m0, s43
	s_add_u32 s12, s30, 0x80080
	global_load_lds_dwordx4 v[0:1], off
	v_lshl_add_u64 v[0:1], v[4:5], 0, s[10:11]
	s_mov_b32 m0, s44
	s_addc_u32 s13, s31, 0
	global_load_lds_dwordx4 v[0:1], off
	s_add_i32 m0, s27, 0x1c000
	v_lshl_add_u64 v[0:1], s[12:13], 0, v[130:131]
	global_load_lds_dwordx4 v[0:1], off
	v_lshl_add_u64 v[0:1], s[12:13], 0, v[134:135]
	s_add_i32 m0, s27, 0x1e000
	s_cmpk_lt_u32 s4, 0x100
	global_load_lds_dwordx4 v[0:1], off
	v_lshrrev_b32_e32 v1, 1, v8
	v_and_b32_e32 v1, 24, v1
	v_and_b32_e32 v0, 15, v8
	v_lshlrev_b32_e32 v2, 1, v1
	v_lshl_or_b32 v152, s1, 6, v0
	v_lshl_or_b32 v0, v0, 6, v2
	v_lshlrev_b32_e32 v2, 2, v8
	v_and_b32_e32 v2, 32, v2
	v_bitop3_b32 v3, v0, s0, v2 bitop3:0xde
	v_bitop3_b32 v153, v0, s14, v2 bitop3:0xde
	v_lshlrev_b32_e32 v0, 15, v9
	v_and_b32_e32 v0, 0xffff0000, v0
	v_or_b32_e32 v154, s5, v1
	v_lshl_add_u32 v0, v10, 12, v0
	v_and_b32_e32 v1, 1, v9
	v_lshl_or_b32 v0, v1, 6, v0
	v_lshl_add_u32 v138, v11, 1, v0
	v_lshlrev_b32_e32 v0, 15, v12
	v_and_b32_e32 v0, 0xffff0000, v0
	s_waitcnt vmcnt(8)
	s_barrier
	s_waitcnt vmcnt(6)
	v_lshl_add_u32 v0, v13, 12, v0
	v_and_b32_e32 v1, 1, v12
	s_cselect_b64 s[12:13], -1, 0
	v_lshl_or_b32 v0, v1, 6, v0
	s_add_i32 s47, 0, 0x10000
	s_add_i32 s48, 0, 0x14000
	s_ashr_i32 s45, s76, 31
	s_mov_b32 s46, s76
	v_mov_b32_e32 v139, v137
	v_lshl_add_u32 v140, v14, 1, v0
	v_mov_b32_e32 v141, v137
	v_mov_b64_e32 v[142:143], 0x200
	v_mov_b64_e32 v[144:145], 0x1ff
	v_add_u32_e32 v155, s47, v153
	v_add_u32_e32 v156, s48, v153
	v_add_u32_e32 v157, 0, v3
	s_mov_b32 s49, 0x80000
	s_mov_b64 s[14:15], 0x90000
	s_mov_b32 s50, 0x90000
	s_mov_b64 s[16:17], 0xa0000
	s_mov_b32 s51, 0xa0000
	s_mov_b64 s[18:19], 0xb0000
	s_mov_b32 s33, 0xb0000
	s_barrier
	s_waitcnt vmcnt(0)
	s_branch .LBB0_862

; #define PG8_STAGE(bufoff, gbase, voff) do { _Pragma("unroll") for (int _i = 0; _i < 2; ++_i) \
;         __builtin_amdgcn_global_load_lds((const unsigned*)((const char*)(gbase) + (voff)[_i]), (PG8_LAS unsigned*)(lds + (bufoff) + ldsw + _i * 8192), 16, 0, 0); } while (0)
; #define PG8_WAIT_V(n) asm volatile("s_waitcnt vmcnt(" #n ")" ::: "memory")
; #define PG8_BAR __builtin_amdgcn_s_barrier()
; template <class Epi, class Sched, bool ALIGN_EPI = false, bool SP2 = false>
; __device__ __forceinline__ void gemm_phase(PG8_LAS unsigned char* lds, const Gemm g, const Sched& S, const Epi& E) {
;     ...
;     const unsigned ldsw = (unsigned)wid * 1024u;
;     const int aoff = lds_byte(wr * 64 + fr, fq * 8), boff = lds_byte(wc * 32 + fr, fq * 8);
;     ...
;         PG8_STAGE(PG8_SB(0, 0), cB, voffB); PG8_STAGE(PG8_SB(0, 1), cB + hstep, voffB); PG8_STAGE(PG8_SA(0, 0), cA, voffA); PG8_STAGE(PG8_SA(0, 1), cA + hstep, voffA);
;         if (wr == 1) PG8_BAR;
;         PG8_WAIT_V(2); PG8_BAR;
;         PG8_STAGE(PG8_SB(1, 0), cB + kstep, voffB); PG8_STAGE(PG8_SA(1, 0), cA + kstep, voffA); PG8_STAGE(PG8_SB(1, 1), cB + hstep + kstep, voffB);
;         PG8_WAIT_V(6); PG8_BAR;
.LBB0_935:
	s_lshl_b32 s2, s2, 5
	s_mov_b64 s[8:9], 0x80
	s_and_b32 s12, s2, 0x60
	s_add_i32 m0, s19, 0x18000
	v_lshl_add_u64 v[6:7], v[6:7], 0, s[8:9]
	s_lshl_b32 s5, s1, 13
	s_lshl_b32 s13, s12, 7
	global_load_lds_dwordx4 v[6:7], off
	v_lshl_add_u64 v[4:5], v[4:5], 0, s[8:9]
	s_add_i32 m0, s19, 0x1a000
	s_add_i32 s31, s19, 0x8000
	s_add_i32 s34, s19, 0xa000
	global_load_lds_dwordx4 v[4:5], off
	v_lshl_add_u64 v[0:1], v[0:1], 0, s[8:9]
	s_mov_b32 m0, s31
	s_add_u32 s10, s22, 0x80080
	global_load_lds_dwordx4 v[0:1], off
	v_lshl_add_u64 v[0:1], v[2:3], 0, s[8:9]
	s_mov_b32 m0, s34
	s_addc_u32 s11, s23, 0
	global_load_lds_dwordx4 v[0:1], off
	s_add_i32 m0, s19, 0x1c000
	v_lshl_add_u64 v[0:1], s[10:11], 0, v[130:131]
	global_load_lds_dwordx4 v[0:1], off
	v_lshl_add_u64 v[0:1], s[10:11], 0, v[134:135]
	s_add_i32 m0, s19, 0x1e000
	s_cmpk_lt_u32 s4, 0x100
	global_load_lds_dwordx4 v[0:1], off
	v_lshrrev_b32_e32 v1, 1, v8
	v_and_b32_e32 v1, 24, v1
	v_and_b32_e32 v0, 15, v8
	v_lshlrev_b32_e32 v2, 1, v1
	v_lshl_or_b32 v150, s1, 6, v0
	v_lshl_or_b32 v0, v0, 6, v2
	v_lshlrev_b32_e32 v2, 2, v8
	v_and_b32_e32 v2, 32, v2
	v_bitop3_b32 v3, v0, s5, v2 bitop3:0xde
	v_bitop3_b32 v151, v0, s13, v2 bitop3:0xde
	v_lshlrev_b32_e32 v0, 15, v9
	v_and_b32_e32 v0, 0xffff0000, v0
	v_or_b32_e32 v152, s12, v1
	v_lshl_add_u32 v0, v10, 12, v0
	v_and_b32_e32 v1, 1, v9
	v_lshl_or_b32 v0, v1, 6, v0
	v_lshl_add_u32 v136, v11, 1, v0
	v_lshlrev_b32_e32 v0, 15, v12
	v_and_b32_e32 v0, 0xffff0000, v0
	s_waitcnt vmcnt(8)
	s_barrier
	s_waitcnt vmcnt(6)
	v_lshl_add_u32 v0, v13, 12, v0
	v_and_b32_e32 v1, 1, v12
	s_cselect_b64 s[10:11], -1, 0
	v_lshl_or_b32 v0, v1, 6, v0
	s_add_i32 s37, 0, 0x10000
	s_add_i32 s38, 0, 0x14000
	s_sext_i32_i8 s2, s0
	s_ashr_i32 s35, s76, 31
	s_mov_b32 s36, s76
	v_mov_b32_e32 v137, v131
	v_lshl_add_u32 v138, v14, 1, v0
	v_mov_b32_e32 v139, v131
	v_mov_b64_e32 v[140:141], 0x200
	v_mov_b64_e32 v[142:143], 0x1ff
	v_add_u32_e32 v153, s37, v151
	v_add_u32_e32 v154, s38, v151
	v_add_u32_e32 v155, 0, v3
	s_barrier
	s_branch .LBB0_938

; #define PG8_STAGE(bufoff, gbase, voff) do { _Pragma("unroll") for (int _i = 0; _i < 2; ++_i) \
;         __builtin_amdgcn_global_load_lds((const unsigned*)((const char*)(gbase) + (voff)[_i]), (PG8_LAS unsigned*)(lds + (bufoff) + ldsw + _i * 8192), 16, 0, 0); } while (0)
; #define PG8_WAIT_V(n) asm volatile("s_waitcnt vmcnt(" #n ")" ::: "memory")
; #define PG8_BAR __builtin_amdgcn_s_barrier()
; template <class Epi, class Sched, bool ALIGN_EPI = false, bool SP2 = false>
; __device__ __forceinline__ void gemm_phase(PG8_LAS unsigned char* lds, const Gemm g, const Sched& S, const Epi& E) {
;     ...
;     const unsigned ldsw = (unsigned)wid * 1024u;
;     const int aoff = lds_byte(wr * 64 + fr, fq * 8), boff = lds_byte(wc * 32 + fr, fq * 8);
;     ...
;         PG8_STAGE(PG8_SB(0, 0), cB, voffB); PG8_STAGE(PG8_SB(0, 1), cB + hstep, voffB); PG8_STAGE(PG8_SA(0, 0), cA, voffA); PG8_STAGE(PG8_SA(0, 1), cA + hstep, voffA);
;         if (wr == 1) PG8_BAR;
;         PG8_WAIT_V(2); PG8_BAR;
;         PG8_STAGE(PG8_SB(1, 0), cB + kstep, voffB); PG8_STAGE(PG8_SA(1, 0), cA + kstep, voffA); PG8_STAGE(PG8_SB(1, 1), cB + hstep + kstep, voffB);
;         PG8_WAIT_V(6); PG8_BAR;
.LBB0_1007:
	s_lshl_b32 s8, s8, 5
	s_and_b32 s14, s8, 0x60
	s_mov_b64 s[8:9], 0x80
	s_add_i32 m0, s19, 0x18000
	v_lshl_add_u64 v[6:7], v[6:7], 0, s[8:9]
	s_lshl_b32 s11, s10, 13
	s_lshl_b32 s15, s14, 7
	global_load_lds_dwordx4 v[6:7], off
	v_lshl_add_u64 v[2:3], v[2:3], 0, s[8:9]
	s_add_i32 m0, s19, 0x1a000
	s_add_i32 s39, s19, 0x8000
	s_add_i32 s40, s19, 0xa000
	global_load_lds_dwordx4 v[2:3], off
	v_lshl_add_u64 v[0:1], v[0:1], 0, s[8:9]
	s_mov_b32 m0, s39
	s_add_u32 s12, s30, 0x80080
	global_load_lds_dwordx4 v[0:1], off
	v_lshl_add_u64 v[0:1], v[4:5], 0, s[8:9]
	s_mov_b32 m0, s40
	s_addc_u32 s13, s31, 0
	global_load_lds_dwordx4 v[0:1], off
	s_add_i32 m0, s19, 0x1c000
	v_lshl_add_u64 v[0:1], s[12:13], 0, v[132:133]
	global_load_lds_dwordx4 v[0:1], off
	v_lshl_add_u64 v[0:1], s[12:13], 0, v[128:129]
	s_add_i32 m0, s19, 0x1e000
	s_cmpk_lt_u32 s5, 0x100
	global_load_lds_dwordx4 v[0:1], off
	v_lshrrev_b32_e32 v1, 1, v10
	v_and_b32_e32 v1, 24, v1
	v_and_b32_e32 v0, 15, v10
	v_lshlrev_b32_e32 v2, 1, v1
	v_lshl_or_b32 v144, s10, 6, v0
	v_lshl_or_b32 v0, v0, 6, v2
	v_lshlrev_b32_e32 v2, 2, v10
	v_and_b32_e32 v2, 32, v2
	v_bitop3_b32 v3, v0, s11, v2 bitop3:0xde
	v_bitop3_b32 v145, v0, s15, v2 bitop3:0xde
	v_lshlrev_b32_e32 v0, 15, v13
	v_and_b32_e32 v0, 0xffff0000, v0
	v_or_b32_e32 v146, s14, v1
	v_lshl_add_u32 v0, v12, 12, v0
	v_and_b32_e32 v1, 1, v13
	v_lshl_or_b32 v0, v1, 6, v0
	v_lshl_add_u32 v136, v14, 1, v0
	v_lshlrev_b32_e32 v0, 15, v8
	v_and_b32_e32 v0, 0xffff0000, v0
	s_waitcnt vmcnt(8)
	s_barrier
	s_waitcnt vmcnt(6)
	v_lshl_add_u32 v0, v9, 12, v0
	v_and_b32_e32 v1, 1, v8
	s_cselect_b64 s[10:11], -1, 0
	v_lshl_or_b32 v0, v1, 6, v0
	s_add_i32 s43, 0, 0x10000
	s_add_i32 s44, 0, 0x14000
	s_sext_i32_i8 s49, s4
	s_ashr_i32 s41, s76, 31
	s_mov_b32 s42, s76
	v_mov_b32_e32 v137, v133
	v_lshl_add_u32 v138, v11, 1, v0
	v_mov_b32_e32 v139, v133
	v_mov_b64_e32 v[140:141], 0x200
	v_mov_b64_e32 v[142:143], 0x1ff
	v_add_u32_e32 v147, s43, v145
	v_add_u32_e32 v148, s44, v145
	v_add_u32_e32 v149, 0, v3
	s_mov_b32 s45, 0x80000
	s_mov_b64 s[12:13], 0x90000
	s_mov_b32 s46, 0x90000
	s_mov_b64 s[14:15], 0xa0000
	s_mov_b32 s47, 0xa0000
	s_mov_b64 s[16:17], 0xb0000
	s_mov_b32 s48, 0xb0000
	s_barrier
	s_branch .LBB0_1010

; #define PG8_STAGE(bufoff, gbase, voff) do { _Pragma("unroll") for (int _i = 0; _i < 2; ++_i) \
;         __builtin_amdgcn_global_load_lds((const unsigned*)((const char*)(gbase) + (voff)[_i]), (PG8_LAS unsigned*)(lds + (bufoff) + ldsw + _i * 8192), 16, 0, 0); } while (0)
; #define PG8_WAIT_V(n) asm volatile("s_waitcnt vmcnt(" #n ")" ::: "memory")
; #define PG8_BAR __builtin_amdgcn_s_barrier()
; template <class Epi, class Sched, bool ALIGN_EPI = false, bool SP2 = false>
; __device__ __forceinline__ void gemm_phase(PG8_LAS unsigned char* lds, const Gemm g, const Sched& S, const Epi& E) {
;     ...
;     const unsigned ldsw = (unsigned)wid * 1024u;
;     const int aoff = lds_byte(wr * 64 + fr, fq * 8), boff = lds_byte(wc * 32 + fr, fq * 8);
;     ...
;         PG8_STAGE(PG8_SB(0, 0), cB, voffB); PG8_STAGE(PG8_SB(0, 1), cB + hstep, voffB); PG8_STAGE(PG8_SA(0, 0), cA, voffA); PG8_STAGE(PG8_SA(0, 1), cA + hstep, voffA);
;         if (wr == 1) PG8_BAR;
;         PG8_WAIT_V(2); PG8_BAR;
;         PG8_STAGE(PG8_SB(1, 0), cB + kstep, voffB); PG8_STAGE(PG8_SA(1, 0), cA + kstep, voffA); PG8_STAGE(PG8_SB(1, 1), cB + hstep + kstep, voffB);
;         PG8_WAIT_V(6); PG8_BAR;
.LBB0_1132:
	s_lshl_b32 s6, s6, 5
	s_and_b32 s12, s6, 0x60
	s_mov_b64 s[6:7], 0x80
	s_add_i32 m0, s19, 0x18000
	v_lshl_add_u64 v[6:7], v[6:7], 0, s[6:7]
	s_lshl_b32 s9, s8, 13
	s_lshl_b32 s13, s12, 7
	global_load_lds_dwordx4 v[6:7], off
	v_lshl_add_u64 v[4:5], v[4:5], 0, s[6:7]
	s_add_i32 m0, s19, 0x1a000
	s_add_i32 s34, s19, 0x8000
	s_add_i32 s35, s19, 0xa000
	global_load_lds_dwordx4 v[4:5], off
	v_lshl_add_u64 v[0:1], v[0:1], 0, s[6:7]
	s_mov_b32 m0, s34
	s_add_u32 s10, s22, 0x80080
	global_load_lds_dwordx4 v[0:1], off
	v_lshl_add_u64 v[0:1], v[2:3], 0, s[6:7]
	s_mov_b32 m0, s35
	s_addc_u32 s11, s23, 0
	global_load_lds_dwordx4 v[0:1], off
	s_add_i32 m0, s19, 0x1c000
	v_lshl_add_u64 v[0:1], s[10:11], 0, v[132:133]
	global_load_lds_dwordx4 v[0:1], off
	v_lshl_add_u64 v[0:1], s[10:11], 0, v[128:129]
	s_add_i32 m0, s19, 0x1e000
	s_cmpk_lt_u32 s5, 0x100
	global_load_lds_dwordx4 v[0:1], off
	v_lshrrev_b32_e32 v1, 1, v9
	v_and_b32_e32 v1, 24, v1
	v_and_b32_e32 v0, 15, v9
	v_lshlrev_b32_e32 v2, 1, v1
	v_lshl_or_b32 v144, s8, 6, v0
	v_lshl_or_b32 v0, v0, 6, v2
	v_lshlrev_b32_e32 v2, 2, v9
	v_and_b32_e32 v2, 32, v2
	v_bitop3_b32 v3, v0, s9, v2 bitop3:0xde
	v_bitop3_b32 v145, v0, s13, v2 bitop3:0xde
	v_lshlrev_b32_e32 v0, 15, v13
	v_and_b32_e32 v0, 0xffff0000, v0
	v_or_b32_e32 v146, s12, v1
	v_lshl_add_u32 v0, v12, 12, v0
	v_and_b32_e32 v1, 1, v13
	v_lshl_or_b32 v0, v1, 6, v0
	v_lshl_add_u32 v136, v14, 1, v0
	v_lshlrev_b32_e32 v0, 15, v8
	v_and_b32_e32 v0, 0xffff0000, v0
	s_waitcnt vmcnt(8)
	s_barrier
	s_waitcnt vmcnt(6)
	v_lshl_add_u32 v0, v10, 12, v0
	v_and_b32_e32 v1, 1, v8
	s_cselect_b64 s[8:9], -1, 0
	v_lshl_or_b32 v0, v1, 6, v0
	s_add_i32 s38, 0, 0x10000
	s_add_i32 s39, 0, 0x14000
	s_sext_i32_i16 s41, s4
	s_ashr_i32 s36, s76, 31
	s_mov_b32 s37, s76
	v_mov_b32_e32 v137, v133
	v_lshl_add_u32 v138, v11, 1, v0
	v_mov_b32_e32 v139, v133
	v_mov_b64_e32 v[140:141], 0xb00
	v_mov_b64_e32 v[142:143], 0xaff
	v_add_u32_e32 v147, s38, v145
	v_add_u32_e32 v148, s39, v145
	v_add_u32_e32 v149, 0, v3
	s_movk_i32 s40, 0x2c00
	s_barrier
	s_branch .LBB0_1135

; #define PG8_STAGE(bufoff, gbase, voff) do { _Pragma("unroll") for (int _i = 0; _i < 2; ++_i) \
;         __builtin_amdgcn_global_load_lds((const unsigned*)((const char*)(gbase) + (voff)[_i]), (PG8_LAS unsigned*)(lds + (bufoff) + ldsw + _i * 8192), 16, 0, 0); } while (0)
; #define PG8_WAIT_V(n) asm volatile("s_waitcnt vmcnt(" #n ")" ::: "memory")
; #define PG8_BAR __builtin_amdgcn_s_barrier()
; template <class Epi, class Sched, bool ALIGN_EPI = false, bool SP2 = false>
; __device__ __forceinline__ void gemm_phase(PG8_LAS unsigned char* lds, const Gemm g, const Sched& S, const Epi& E) {
;     ...
;     for (int i = 0; i < 2; ++i) { int R, C; stage_rc(tid * 16 + i * 8192, R, C); const int Rb = Epi::PERM ? ((R & ~31) + perm32(R & 31)) : R;
;         voffA[i] = (unsigned)(R * K + C) * 2u; voffB[i] = (unsigned)(Rb * K + C) * 2u; }
;     const size_t kstep = (size_t)(BK * 2);
;     const size_t hstep = (size_t)HALF * K * 2;
;     const size_t tstep = 2 * hstep;
;     const unsigned ldsw = (unsigned)wid * 1024u;
;     const int aoff = lds_byte(wr * 64 + fr, fq * 8), boff = lds_byte(wc * 32 + fr, fq * 8);
;     ...
;         PG8_STAGE(PG8_SB(0, 0), cB, voffB); PG8_STAGE(PG8_SB(0, 1), cB + hstep, voffB); PG8_STAGE(PG8_SA(0, 0), cA, voffA); PG8_STAGE(PG8_SA(0, 1), cA + hstep, voffA);
;         if (wr == 1) PG8_BAR;
;         PG8_WAIT_V(2); PG8_BAR;
;         PG8_STAGE(PG8_SB(1, 0), cB + kstep, voffB); PG8_STAGE(PG8_SA(1, 0), cA + kstep, voffA); PG8_STAGE(PG8_SB(1, 1), cB + hstep + kstep, voffB);
;         PG8_WAIT_V(6); PG8_BAR;
.LBB0_1200:
	s_lshl_b32 s7, s7, 5
	s_mov_b64 s[8:9], 0x80
	s_and_b32 s13, s7, 0x60
	s_add_i32 m0, s30, 0x18000
	v_lshl_add_u64 v[6:7], v[6:7], 0, s[8:9]
	s_lshl_b32 s11, s6, 13
	s_lshl_b32 s7, s13, 7
	global_load_lds_dwordx4 v[6:7], off
	v_lshl_add_u64 v[2:3], v[2:3], 0, s[8:9]
	s_add_i32 m0, s30, 0x1a000
	s_add_i32 s36, s30, 0x8000
	s_add_i32 s37, s30, 0xa000
	global_load_lds_dwordx4 v[2:3], off
	v_lshl_add_u64 v[0:1], v[0:1], 0, s[8:9]
	s_mov_b32 m0, s36
	s_add_u32 s14, s24, 0x160080
	global_load_lds_dwordx4 v[0:1], off
	v_lshl_add_u64 v[0:1], v[4:5], 0, s[8:9]
	s_mov_b32 m0, s37
	s_addc_u32 s15, s25, 0
	global_load_lds_dwordx4 v[0:1], off
	s_add_i32 m0, s30, 0x1c000
	v_lshl_add_u64 v[0:1], s[14:15], 0, v[132:133]
	global_load_lds_dwordx4 v[0:1], off
	v_lshl_add_u64 v[0:1], s[14:15], 0, v[128:129]
	s_add_i32 m0, s30, 0x1e000
	s_cmpk_lt_u32 s4, 0x100
	global_load_lds_dwordx4 v[0:1], off
	v_lshrrev_b32_e32 v1, 1, v10
	v_and_b32_e32 v1, 24, v1
	v_and_b32_e32 v0, 15, v10
	v_lshlrev_b32_e32 v2, 1, v1
	v_lshl_or_b32 v144, s6, 6, v0
	v_lshl_or_b32 v0, v0, 6, v2
	v_lshlrev_b32_e32 v2, 2, v10
	v_and_b32_e32 v2, 32, v2
	v_bitop3_b32 v3, v0, s11, v2 bitop3:0xde
	v_bitop3_b32 v145, v0, s7, v2 bitop3:0xde
	v_or_b32_e32 v146, s13, v1
	v_lshrrev_b32_e32 v1, 1, v14
	v_mul_lo_u32 v0, v13, s5
	v_mad_u64_u32 v[0:1], s[14:15], v1, s12, v[0:1]
	v_or_b32_e32 v0, v0, v15
	s_mov_b64 s[6:7], 0x160080
	v_add_lshl_u32 v0, v0, v16, 1
	v_mov_b32_e32 v1, v133
	v_lshl_add_u64 v[136:137], v[0:1], 0, s[6:7]
	v_lshrrev_b32_e32 v1, 1, v8
	v_mul_lo_u32 v0, v9, s5
	v_mad_u64_u32 v[0:1], s[4:5], v1, s12, v[0:1]
	s_waitcnt vmcnt(8)
	s_barrier
	s_waitcnt vmcnt(6)
	v_or_b32_e32 v0, v0, v11
	s_sext_i32_i8 s49, s10
	s_cselect_b64 s[10:11], -1, 0
	v_add_lshl_u32 v0, v0, v12, 1
	v_mov_b32_e32 v1, v133
	s_add_i32 s40, 0, 0x10000
	s_add_i32 s41, 0, 0x14000
	s_ashr_i32 s38, s76, 31
	s_mov_b32 s39, s76
	v_lshl_add_u64 v[138:139], v[0:1], 0, s[6:7]
	v_mov_b64_e32 v[140:141], 0x200
	v_mov_b64_e32 v[142:143], 0x1ff
	v_add_u32_e32 v147, s40, v145
	v_add_u32_e32 v148, s41, v145
	v_add_u32_e32 v149, 0, v3
	s_mov_b64 s[12:13], 0x80000
	s_mov_b32 s42, 0x80000
	s_mov_b64 s[14:15], 0x90000
	s_mov_b32 s43, 0x90000
	s_mov_b64 s[16:17], 0xa0000
	s_mov_b32 s44, 0xa0000
	s_mov_b64 s[18:19], 0xb0000
	s_mov_b32 s45, 0xb0000
	s_barrier
	s_branch .LBB0_1203
